# attention: lane^32 exchanges via v_permlane32_swap instead of ds_bpermute (fast steps and gate loop)
# baseline (speedup 1.0000x reference)
; __device__ __forceinline__ float bf2f(unsigned v) { return __uint_as_float(v << 16); }
; __device__ void attn_item(const Params& p, char* lds, int bh, int qi) {
;     ...
;     for (int j = 0; j < qi; ++j) {
;       float g = 0.f;
; #pragma unroll
;       for (int ks = 0; ks < 4; ++ks) {
;         const f32x4 ka = *(const f32x4*)(km + j * 64 + ks * 16 + 8 * h);
;         const f32x4 kb = *(const f32x4*)(km + j * 64 + ks * 16 + 8 * h + 4);
; #pragma unroll
;         for (int e = 0; e < 4; ++e) {
;           g += bf2f((unsigned)(u16)qf[ks][e]) * ka[e];
;           g += bf2f((unsigned)(u16)qf[ks][4 + e]) * kb[e];
;         }
;       }
;       g += __shfl_xor(g, 32);
;       if (g > v0) { v2 = v1; i2 = i1; v1 = v0; i1 = i0; v0 = g; i0 = j; }
;       else if (g > v1) { v2 = v1; i2 = i1; v1 = g; i1 = j; }
;       else if (g > v2) { v2 = g; i2 = j; }
;     }
;     selmask = (1u << i0) | (1u << i1) | (1u << i2);
.LBB0_403:
	ds_read_b128 v[42:45], v36
	ds_read_b128 v[46:49], v36 offset:16
	ds_read_b128 v[50:53], v36 offset:64
	ds_read_b128 v[54:57], v36 offset:80
	s_waitcnt lgkmcnt(3)
	v_fma_f32 v58, v42, v15, 0
	s_waitcnt lgkmcnt(2)
	v_fmac_f32_e32 v58, v46, v16
	v_fmac_f32_e32 v58, v43, v17
	v_fmac_f32_e32 v58, v47, v18
	v_fmac_f32_e32 v58, v44, v19
	v_fmac_f32_e32 v58, v48, v20
	v_fmac_f32_e32 v58, v45, v21
	v_fmac_f32_e32 v58, v49, v22
	s_waitcnt lgkmcnt(1)
	v_fmac_f32_e32 v58, v50, v23
	s_waitcnt lgkmcnt(0)
	v_fmac_f32_e32 v58, v54, v24
	v_fmac_f32_e32 v58, v51, v25
	v_fmac_f32_e32 v58, v55, v26
	v_fmac_f32_e32 v58, v52, v27
	ds_read_b128 v[42:45], v36 offset:128
	ds_read_b128 v[46:49], v36 offset:144
	v_fmac_f32_e32 v58, v56, v28
	v_fmac_f32_e32 v58, v53, v29
	v_fmac_f32_e32 v58, v57, v30
	s_waitcnt lgkmcnt(1)
	v_fmac_f32_e32 v58, v42, v31
	s_waitcnt lgkmcnt(0)
	v_fmac_f32_e32 v58, v46, v32
	v_fmac_f32_e32 v58, v43, v33
	v_mov_b32_e32 v42, v48
	v_mov_b32_e32 v43, v44
	ds_read_b128 v[50:53], v36 offset:192
	ds_read_b128 v[54:57], v36 offset:208
	v_fmac_f32_e32 v58, v47, v35
	v_pk_mul_f32 v[42:43], v[42:43], v[2:3]
	v_mov_b32_e32 v44, v49
	v_add_f32_e32 v43, v43, v58
	v_add_f32_e32 v46, v42, v43
	v_pk_mul_f32 v[42:43], v[44:45], v[4:5]
	v_mov_b32_e32 v45, v37
	v_add_f32_e32 v43, v43, v46
	v_add_f32_e32 v44, v42, v43
	s_waitcnt lgkmcnt(0)
	v_mov_b32_e32 v42, v54
	v_mov_b32_e32 v43, v50
	v_pk_mul_f32 v[42:43], v[42:43], v[6:7]
	v_mov_b32_e32 v50, v55
	v_add_f32_e32 v43, v43, v44
	v_add_f32_e32 v44, v42, v43
	v_pk_mul_f32 v[42:43], v[50:51], v[8:9]
	s_nop 0
	v_add_f32_e32 v43, v43, v44
	v_add_f32_e32 v44, v42, v43
	v_mov_b32_e32 v42, v56
	v_mov_b32_e32 v43, v52
	v_pk_mul_f32 v[42:43], v[42:43], v[10:11]
	v_mov_b32_e32 v52, v57
	v_add_f32_e32 v43, v43, v44
	v_add_f32_e32 v44, v42, v43
	v_pk_mul_f32 v[42:43], v[52:53], v[12:13]
	s_nop 0
	v_add_f32_e32 v43, v43, v44
	v_add_f32_e32 v42, v42, v43
	v_mov_b32_e32 v43, v42
	v_mov_b32_e32 v44, s5
	s_nop 1
	v_permlane32_swap_b32_e32 v42, v43
	v_add_f32_e32 v42, v42, v43
	v_cmp_ngt_f32_e32 vcc, v42, v37
	v_mov_b32_e32 v43, v34
	s_and_saveexec_b64 s[14:15], vcc
	s_cbranch_execz .LBB0_409
	v_cmp_ngt_f32_e32 vcc, v42, v38
	v_mov_b32_e32 v43, s5
	s_and_saveexec_b64 s[18:19], vcc
	s_cbranch_execz .LBB0_408
	v_cmp_gt_f32_e32 vcc, v42, v41
	s_and_saveexec_b64 s[20:21], vcc
	v_mov_b32_e32 v40, s5
	v_mov_b32_e32 v41, v42
	s_or_b64 exec, exec, s[20:21]
	v_mov_b32_e32 v42, v38
	v_mov_b32_e32 v38, v41
	v_mov_b32_e32 v43, v39
	v_mov_b32_e32 v39, v40

; __device__ void attn_item(const Params& p, char* lds, int bh, int qi) {
;     ...
;     S0 = __builtin_amdgcn_mfma_f32_32x32x16_bf16(*(const bf16x8*)(ks_), qf[0], cb, 0, 0, 0);
; #pragma unroll
;     for (int ks = 1; ks < 4; ++ks) S0 = __builtin_amdgcn_mfma_f32_32x32x16_bf16(*(const bf16x8*)(ks_ + ks * 16), qf[ks], S0, 0, 0, 0);
;     S1 = __builtin_amdgcn_mfma_f32_32x32x16_bf16(*(const bf16x8*)(ks_ + 32 * LD), qf[0], cb, 0, 0, 0);
; #pragma unroll
;     for (int ks = 1; ks < 4; ++ks) S1 = __builtin_amdgcn_mfma_f32_32x32x16_bf16(*(const bf16x8*)(ks_ + 32 * LD + ks * 16), qf[ks], S1, 0, 0, 0);
;     if constexpr (DIAG) {
;       const int qrel = wave * 32 + l31;
; #pragma unroll
;       for (int r = 0; r < 16; ++r) {
;         const int krel = sub * 64 + rm32(r, h);
;         S0[r] = (krel <= qrel) ? S0[r] : -INFINITY;
;         S1[r] = (krel + 32 <= qrel) ? S1[r] : -INFINITY;
;       }
;     }
;     float mx0 = -INFINITY, mx1 = -INFINITY, ps0 = 0.f, ps1 = 0.f;
; #pragma unroll
;     for (int r = 0; r < 16; r += 2) mx0 = fmaxf(fmaxf(mx0, S0[r]), S0[r + 1]);
; #pragma unroll
;     for (int r = 0; r < 16; ++r) { S0[r] = __builtin_amdgcn_exp2f(S0[r]); ps0 += S0[r]; }
; #pragma unroll
;     for (int sp = 0; sp < 2; ++sp) {
;       u32x4 pw;
;       pw.x = pk2(S0[8 * sp + 0], S0[8 * sp + 1]); pw.y = pk2(S0[8 * sp + 2], S0[8 * sp + 3]);
;       pw.z = pk2(S0[8 * sp + 4], S0[8 * sp + 5]); pw.w = pk2(S0[8 * sp + 6], S0[8 * sp + 7]);
;       const bf16x8 pb = __builtin_bit_cast(bf16x8, pw);
; #pragma unroll
;       for (int d = 0; d < 2; ++d) O[d] = __builtin_amdgcn_mfma_f32_32x32x16_bf16(*(const bf16x8*)(vs_ + d * 32 * LD + sp * 16), pb, O[d], 0, 0, 0);
;     }
; #pragma unroll
;     for (int r = 0; r < 16; r += 2) mx1 = fmaxf(fmaxf(mx1, S1[r]), S1[r + 1]);
; #pragma unroll
;     for (int r = 0; r < 16; ++r) { S1[r] = __builtin_amdgcn_exp2f(S1[r]); ps1 += S1[r]; }
; #pragma unroll
;     for (int sp = 0; sp < 2; ++sp) {
;       u32x4 pw;
;       pw.x = pk2(S1[8 * sp + 0], S1[8 * sp + 1]); pw.y = pk2(S1[8 * sp + 2], S1[8 * sp + 3]);
;       pw.z = pk2(S1[8 * sp + 4], S1[8 * sp + 5]); pw.w = pk2(S1[8 * sp + 6], S1[8 * sp + 7]);
;       const bf16x8 pb = __builtin_bit_cast(bf16x8, pw);
; #pragma unroll
;       for (int d = 0; d < 2; ++d) O[d] = __builtin_amdgcn_mfma_f32_32x32x16_bf16(*(const bf16x8*)(vs_ + d * 32 * LD + 32 + sp * 16), pb, O[d], 0, 0, 0);
;     }
.LBB0_436:
	s_and_b32 s26, s6, 64
	s_mulk_i32 s26, 0x90
	v_add_u32_e32 v127, s26, v119
	ds_read_b128 v[90:93], v127 offset:4672
	s_add_i32 s26, s6, 63
	v_cmp_le_u32_e32 vcc, s26, v112
	s_xor_b64 s[22:23], s[22:23], -1
	s_or_b64 s[22:23], s[22:23], vcc
	s_and_saveexec_b64 s[26:27], s[22:23]
	s_xor_b64 s[22:23], exec, s[26:27]
	s_cbranch_execz .LBB0_440
	ds_read_b128 v[128:131], v127
	ds_read_b128 v[132:135], v127 offset:32
	v_cndmask_b32_e64 v50, v125, -v107, s[24:25]
	v_mov_b32_e32 v51, v50
	v_mov_b32_e32 v52, v50
	v_mov_b32_e32 v53, v50
	v_mov_b32_e32 v54, v50
	v_mov_b32_e32 v55, v50
	v_mov_b32_e32 v56, v50
	v_mov_b32_e32 v57, v50
	v_mov_b32_e32 v58, v50
	v_mov_b32_e32 v59, v50
	v_mov_b32_e32 v60, v50
	v_mov_b32_e32 v61, v50
	v_mov_b32_e32 v62, v50
	v_mov_b32_e32 v63, v50
	v_mov_b32_e32 v64, v50
	v_mov_b32_e32 v65, v50
	v_cmp_lt_i32_e32 vcc, v156, v157
	s_waitcnt lgkmcnt(1)
	v_mfma_f32_32x32x16_bf16 v[34:49], v[128:131], v[66:69], v[50:65]
	ds_read_b128 v[128:131], v127 offset:4608
	ds_read_b128 v[136:139], v127 offset:4640
	s_waitcnt lgkmcnt(2)
	v_mfma_f32_32x32x16_bf16 v[34:49], v[132:135], v[70:73], v[34:49]
	s_waitcnt lgkmcnt(1)
	v_mfma_f32_32x32x16_bf16 v[50:65], v[128:131], v[66:69], v[50:65]
	ds_read_b128 v[128:131], v127 offset:64
	ds_read_b128 v[132:135], v127 offset:96
	s_waitcnt lgkmcnt(1)
	v_mfma_f32_32x32x16_bf16 v[34:49], v[128:131], v[74:77], v[34:49]
	ds_read_b128 v[128:131], v127 offset:4704
	v_mfma_f32_32x32x16_bf16 v[50:65], v[136:139], v[70:73], v[50:65]
	s_waitcnt lgkmcnt(1)
	v_mfma_f32_32x32x16_bf16 v[34:49], v[132:135], v[78:81], v[34:49]
	v_mfma_f32_32x32x16_bf16 v[50:65], v[90:93], v[74:77], v[50:65]
	s_nop 10
	v_exp_f32_e32 v140, v34
	v_max_f32_e32 v34, v34, v34
	v_max_f32_e32 v34, 0xff800000, v34
	v_max3_f32 v34, v34, v35, v36
	v_max3_f32 v34, v34, v37, v38
	v_max3_f32 v34, v34, v39, v40
	v_max3_f32 v34, v34, v41, v42
	s_waitcnt lgkmcnt(0)
	v_mfma_f32_32x32x16_bf16 v[50:65], v[128:131], v[78:81], v[50:65]
	v_exp_f32_e32 v142, v35
	v_exp_f32_e32 v144, v36
	v_exp_f32_e32 v146, v37
	v_exp_f32_e32 v148, v38
	v_exp_f32_e32 v150, v39
	v_exp_f32_e32 v152, v40
	v_exp_f32_e32 v154, v41
	v_max3_f32 v34, v34, v43, v44
	v_exp_f32_e32 v158, v42
	v_exp_f32_e32 v160, v43
	v_exp_f32_e32 v162, v44
	v_exp_f32_e32 v164, v45
	v_max3_f32 v34, v34, v45, v46
	ds_read_b128 v[38:41], v127 offset:18432
	ds_read_b128 v[42:45], v127 offset:23040
	v_exp_f32_e32 v170, v48
	v_max3_f32 v48, v34, v47, v48
	v_cvt_pk_bf16_f32 v34, v140, v142
	v_cvt_pk_bf16_f32 v35, v144, v146
	v_cvt_pk_bf16_f32 v36, v148, v150
	v_cvt_pk_bf16_f32 v37, v152, v154
	v_exp_f32_e32 v166, v46
	v_max3_f32 v46, v50, s34, v51
	s_waitcnt lgkmcnt(1)
	v_mfma_f32_32x32x16_bf16 v[18:33], v[38:41], v[34:37], v[18:33]
	v_max3_f32 v46, v46, v52, v53
	v_exp_f32_e32 v141, v50
	v_max3_f32 v38, v46, v54, v55
	v_exp_f32_e32 v143, v51
	v_exp_f32_e32 v168, v47
	v_exp_f32_e32 v172, v49
	v_max3_f32 v38, v38, v56, v57
	s_waitcnt lgkmcnt(0)
	v_mfma_f32_32x32x16_bf16 v[2:17], v[42:45], v[34:37], v[2:17]
	v_exp_f32_e32 v145, v52
	ds_read_b128 v[128:131], v127 offset:18464
	ds_read_b128 v[132:135], v127 offset:23072
	v_max3_f32 v38, v38, v58, v59
	v_exp_f32_e32 v147, v53
	v_max3_f32 v38, v38, v60, v61
	v_pk_add_f32 v[34:35], v[140:141], 0 op_sel_hi:[1,0]
	v_max3_f32 v38, v38, v62, v63
	v_pk_add_f32 v[42:43], v[142:143], v[34:35]
	v_cvt_pk_bf16_f32 v90, v158, v160
	v_cvt_pk_bf16_f32 v91, v162, v164
	v_cvt_pk_bf16_f32 v92, v166, v168
	v_cvt_pk_bf16_f32 v93, v170, v172
	v_max3_f32 v136, v38, v64, v65
	ds_read_b128 v[38:41], v127 offset:18528
	ds_read_b128 v[34:37], v127 offset:18496
	v_pk_add_f32 v[42:43], v[144:145], v[42:43]
	s_waitcnt lgkmcnt(3)
	v_mfma_f32_32x32x16_bf16 v[18:33], v[128:131], v[90:93], v[18:33]
	v_add_f32_e64 v46, v146, v42
	v_add_f32_e64 v47, v147, v43
	ds_read_b128 v[42:45], v127 offset:23104
	v_exp_f32_e32 v149, v54
	v_exp_f32_e32 v151, v55
	v_exp_f32_e32 v153, v56
	v_exp_f32_e32 v155, v57
	v_cvt_pk_bf16_f32 v50, v141, v143
	s_waitcnt lgkmcnt(3)
	v_mfma_f32_32x32x16_bf16 v[2:17], v[132:135], v[90:93], v[2:17]
	v_cvt_pk_bf16_f32 v51, v145, v147
	v_cvt_pk_bf16_f32 v52, v149, v151
	v_cvt_pk_bf16_f32 v53, v153, v155
	v_exp_f32_e32 v159, v58
	v_exp_f32_e32 v161, v59
	v_exp_f32_e32 v163, v60
	v_exp_f32_e32 v165, v61
	s_waitcnt lgkmcnt(1)
	v_mfma_f32_32x32x16_bf16 v[18:33], v[34:37], v[50:53], v[18:33]
	v_exp_f32_e32 v167, v62
	v_exp_f32_e32 v169, v63
	v_exp_f32_e32 v171, v64
	v_exp_f32_e32 v173, v65
	v_pk_add_f32 v[46:47], v[148:149], v[46:47]
	v_cvt_pk_bf16_f32 v34, v159, v161
	v_pk_add_f32 v[46:47], v[150:151], v[46:47]
	s_waitcnt lgkmcnt(0)
	v_mfma_f32_32x32x16_bf16 v[2:17], v[42:45], v[50:53], v[2:17]
	ds_read_b128 v[42:45], v127 offset:23136
	v_add_f32_e64 v46, v152, v46
	v_add_f32_e64 v47, v153, v47
	v_cvt_pk_bf16_f32 v35, v163, v165
	v_cvt_pk_bf16_f32 v36, v167, v169
	v_cvt_pk_bf16_f32 v37, v171, v173
	v_pk_add_f32 v[46:47], v[154:155], v[46:47]
	s_nop 0
	v_mfma_f32_32x32x16_bf16 v[18:33], v[38:41], v[34:37], v[18:33]
	v_add_f32_e64 v38, v158, v46
	v_add_f32_e64 v39, v159, v47
	v_max3_f32 v40, v48, v49, v136
	v_add_f32_e64 v38, v160, v38
	v_add_f32_e64 v39, v161, v39
	v_pk_add_f32 v[38:39], v[162:163], v[38:39]
	s_nop 0
	v_pk_add_f32 v[38:39], v[164:165], v[38:39]
	s_waitcnt lgkmcnt(0)
	v_mfma_f32_32x32x16_bf16 v[2:17], v[42:45], v[34:37], v[2:17]
	v_add_f32_e64 v38, v166, v38
	v_add_f32_e64 v39, v167, v39
	v_mov_b32_e32 v36, v40
	v_pk_add_f32 v[38:39], v[168:169], v[38:39]
	s_nop 0
	v_pk_add_f32 v[34:35], v[170:171], v[38:39]
	s_nop 0
	v_pk_add_f32 v[34:35], v[172:173], v[34:35]
	s_nop 0
	v_add_f32_e32 v34, v34, v35
	v_add_f32_e32 v126, v126, v34
	s_nop 0
	v_permlane32_swap_b32_e32 v40, v36
	v_max_f32_e32 v34, v36, v36
	v_max_f32_e32 v34, v40, v34
	v_cmp_lt_f32_e32 vcc, s35, v34
	s_cbranch_vccz .LBB0_439
	s_nop 0
	v_cndmask_b32_e32 v35, 0, v34, vcc
	v_exp_f32_e64 v34, -v35
	v_add_f32_e32 v107, v107, v35
	v_mul_f32_e32 v126, v126, v34
	v_pk_mul_f32 v[32:33], v[32:33], v[34:35] op_sel_hi:[1,0]
	v_pk_mul_f32 v[30:31], v[30:31], v[34:35] op_sel_hi:[1,0]
	v_pk_mul_f32 v[28:29], v[28:29], v[34:35] op_sel_hi:[1,0]
	v_pk_mul_f32 v[26:27], v[26:27], v[34:35] op_sel_hi:[1,0]
	v_pk_mul_f32 v[24:25], v[24:25], v[34:35] op_sel_hi:[1,0]
	v_pk_mul_f32 v[22:23], v[22:23], v[34:35] op_sel_hi:[1,0]
	v_pk_mul_f32 v[20:21], v[20:21], v[34:35] op_sel_hi:[1,0]
	v_pk_mul_f32 v[18:19], v[18:19], v[34:35] op_sel_hi:[1,0]
	v_pk_mul_f32 v[16:17], v[16:17], v[34:35] op_sel_hi:[1,0]
	v_pk_mul_f32 v[14:15], v[14:15], v[34:35] op_sel_hi:[1,0]
	v_pk_mul_f32 v[12:13], v[12:13], v[34:35] op_sel_hi:[1,0]
	v_pk_mul_f32 v[10:11], v[10:11], v[34:35] op_sel_hi:[1,0]
	v_pk_mul_f32 v[8:9], v[8:9], v[34:35] op_sel_hi:[1,0]
	v_pk_mul_f32 v[6:7], v[6:7], v[34:35] op_sel_hi:[1,0]
	v_pk_mul_f32 v[4:5], v[4:5], v[34:35] op_sel_hi:[1,0]
	v_pk_mul_f32 v[2:3], v[2:3], v[34:35] op_sel_hi:[1,0]
; __device__ __forceinline__ int rm32(int reg, int h) { return (reg & 3) + 8 * (reg >> 2) + 4 * h; }
; __device__ void attn_item(const Params& p, char* lds, int bh, int qi) {
;     ...
;     S0 = __builtin_amdgcn_mfma_f32_32x32x16_bf16(*(const bf16x8*)(ks_), qf[0], cb, 0, 0, 0);
; #pragma unroll
;     for (int ks = 1; ks < 4; ++ks) S0 = __builtin_amdgcn_mfma_f32_32x32x16_bf16(*(const bf16x8*)(ks_ + ks * 16), qf[ks], S0, 0, 0, 0);
;     S1 = __builtin_amdgcn_mfma_f32_32x32x16_bf16(*(const bf16x8*)(ks_ + 32 * LD), qf[0], cb, 0, 0, 0);
; #pragma unroll
;     for (int ks = 1; ks < 4; ++ks) S1 = __builtin_amdgcn_mfma_f32_32x32x16_bf16(*(const bf16x8*)(ks_ + 32 * LD + ks * 16), qf[ks], S1, 0, 0, 0);
;     if constexpr (DIAG) {
;       const int qrel = wave * 32 + l31;
; #pragma unroll
;       for (int r = 0; r < 16; ++r) {
;         const int krel = sub * 64 + rm32(r, h);
;         S0[r] = (krel <= qrel) ? S0[r] : -INFINITY;
;         S1[r] = (krel + 32 <= qrel) ? S1[r] : -INFINITY;
;       }
;     }
;     float mx0 = -INFINITY, mx1 = -INFINITY, ps0 = 0.f, ps1 = 0.f;
; #pragma unroll
;     for (int r = 0; r < 16; r += 2) mx0 = fmaxf(fmaxf(mx0, S0[r]), S0[r + 1]);
; #pragma unroll
;     for (int r = 0; r < 16; ++r) { S0[r] = __builtin_amdgcn_exp2f(S0[r]); ps0 += S0[r]; }
.LBB0_439:
.LBB0_440:
	s_andn2_saveexec_b64 s[22:23], s[22:23]
	s_cbranch_execz .LBB0_443
	ds_read_b128 v[128:131], v127
	ds_read_b128 v[132:135], v127 offset:32
	v_xor_b32_e32 v34, 0x80000000, v107
	v_mov_b32_e32 v35, v34
	v_mov_b32_e32 v36, v34
	v_mov_b32_e32 v37, v34
	v_mov_b32_e32 v38, v34
	v_mov_b32_e32 v39, v34
	v_mov_b32_e32 v40, v34
	v_mov_b32_e32 v41, v34
	v_mov_b32_e32 v42, v34
	v_mov_b32_e32 v43, v34
	v_mov_b32_e32 v44, v34
	v_mov_b32_e32 v45, v34
	v_mov_b32_e32 v46, v34
	v_mov_b32_e32 v47, v34
	v_mov_b32_e32 v48, v34
	v_mov_b32_e32 v49, v34
	s_waitcnt lgkmcnt(1)
	s_nop 0
	v_mfma_f32_32x32x16_bf16 v[50:65], v[128:131], v[66:69], v[34:49]
	ds_read_b128 v[128:131], v127 offset:4608
	ds_read_b128 v[136:139], v127 offset:4640
	s_waitcnt lgkmcnt(1)
	v_mfma_f32_32x32x16_bf16 v[34:49], v[128:131], v[66:69], v[34:49]
	s_waitcnt lgkmcnt(0)
	v_mfma_f32_32x32x16_bf16 v[34:49], v[136:139], v[70:73], v[34:49]
	v_mfma_f32_32x32x16_bf16 v[50:65], v[132:135], v[70:73], v[50:65]
	v_add_u32_e32 v132, s6, v120
	v_cmp_le_u32_e32 vcc, v132, v113
	v_add_u32_e32 v133, 32, v132
	v_mfma_f32_32x32x16_bf16 v[34:49], v[90:93], v[74:77], v[34:49]
	ds_read_b128 v[90:93], v127 offset:64
	ds_read_b128 v[128:131], v127 offset:96
	s_waitcnt lgkmcnt(1)
	v_mfma_f32_32x32x16_bf16 v[50:65], v[90:93], v[74:77], v[50:65]
	ds_read_b128 v[90:93], v127 offset:4704
	s_waitcnt lgkmcnt(1)
	v_mfma_f32_32x32x16_bf16 v[50:65], v[128:131], v[78:81], v[50:65]
	ds_read_b128 v[128:131], v127 offset:18432
	s_waitcnt lgkmcnt(1)
	v_mfma_f32_32x32x16_bf16 v[34:49], v[90:93], v[78:81], v[34:49]
	s_nop 8
	v_cndmask_b32_e32 v50, v125, v50, vcc
	v_cmp_le_u32_e32 vcc, v133, v113
	s_nop 1
	v_cndmask_b32_e32 v90, v125, v34, vcc
	v_cmp_lt_u32_e32 vcc, v132, v113
	s_nop 1
	v_cndmask_b32_e32 v34, v125, v51, vcc
	v_add_u32_e32 v51, 33, v132
	v_cmp_le_u32_e32 vcc, v51, v113
	v_add_u32_e32 v51, 34, v132
	s_nop 0
	v_cndmask_b32_e32 v92, v125, v35, vcc
	v_add_u32_e32 v35, 2, v132
	v_cmp_le_u32_e32 vcc, v35, v113
	s_nop 1
	v_cndmask_b32_e32 v35, v125, v52, vcc
	v_cmp_le_u32_e32 vcc, v51, v113
	s_nop 1
	v_cndmask_b32_e32 v134, v125, v36, vcc
	v_add_u32_e32 v36, 3, v132
	v_cmp_le_u32_e32 vcc, v36, v113
	v_add_u32_e32 v36, 35, v132
	s_nop 0
	v_cndmask_b32_e32 v136, v125, v53, vcc
	v_cmp_le_u32_e32 vcc, v36, v113
	v_add_u32_e32 v36, 8, v132
	s_nop 0
	v_cndmask_b32_e32 v138, v125, v37, vcc
	v_cmp_le_u32_e32 vcc, v36, v113
	v_add_u32_e32 v36, 40, v132
	s_nop 0
	v_cndmask_b32_e32 v54, v125, v54, vcc
	v_cmp_le_u32_e32 vcc, v36, v113
	v_add_u32_e32 v36, 9, v132
	s_nop 0
	v_cndmask_b32_e32 v140, v125, v38, vcc
	v_cmp_le_u32_e32 vcc, v36, v113
	v_add_u32_e32 v36, 41, v132
	s_nop 0
	v_cndmask_b32_e32 v142, v125, v55, vcc
	v_cmp_le_u32_e32 vcc, v36, v113
	v_add_u32_e32 v36, 10, v132
	v_exp_f32_e32 v55, v50
	v_cndmask_b32_e32 v144, v125, v39, vcc
	v_cmp_le_u32_e32 vcc, v36, v113
	v_add_u32_e32 v36, 42, v132
	s_nop 0
	v_cndmask_b32_e32 v56, v125, v56, vcc
	v_cmp_le_u32_e32 vcc, v36, v113
	v_add_u32_e32 v36, 11, v132
	v_exp_f32_e32 v91, v56
	v_cndmask_b32_e32 v145, v125, v40, vcc
	v_cmp_le_u32_e32 vcc, v36, v113
	v_add_u32_e32 v36, 43, v132
	s_nop 0
	v_cndmask_b32_e32 v146, v125, v57, vcc
	v_cmp_le_u32_e32 vcc, v36, v113
	v_add_u32_e32 v36, 16, v132
	v_exp_f32_e32 v57, v34
	v_cndmask_b32_e32 v147, v125, v41, vcc
	v_cmp_le_u32_e32 vcc, v36, v113
	v_add_u32_e32 v36, 48, v132
	ds_read_b128 v[38:41], v127 offset:23040
	v_cndmask_b32_e32 v58, v125, v58, vcc
	v_cmp_le_u32_e32 vcc, v36, v113
	v_add_u32_e32 v36, 17, v132
	v_exp_f32_e32 v93, v146
	v_cndmask_b32_e32 v148, v125, v42, vcc
	v_cmp_le_u32_e32 vcc, v36, v113
	v_add_u32_e32 v36, 49, v132
	v_cvt_pk_bf16_f32 v37, v91, v93
	v_cndmask_b32_e32 v149, v125, v59, vcc
	v_cmp_le_u32_e32 vcc, v36, v113
	v_add_u32_e32 v36, 18, v132
	v_exp_f32_e32 v59, v35
	v_cndmask_b32_e32 v150, v125, v43, vcc
	v_cmp_le_u32_e32 vcc, v36, v113
	v_add_u32_e32 v36, 50, v132
	v_exp_f32_e32 v133, v58
	v_cndmask_b32_e32 v60, v125, v60, vcc
	v_cmp_le_u32_e32 vcc, v36, v113
	v_add_u32_e32 v36, 19, v132
	v_exp_f32_e32 v135, v149
	v_cndmask_b32_e32 v151, v125, v44, vcc
	v_cmp_le_u32_e32 vcc, v36, v113
	v_add_u32_e32 v36, 51, v132
	s_nop 0
	v_cndmask_b32_e32 v152, v125, v61, vcc
	v_cmp_le_u32_e32 vcc, v36, v113
	v_add_u32_e32 v36, 24, v132
	v_exp_f32_e32 v61, v136
	v_cndmask_b32_e32 v153, v125, v45, vcc
	v_cmp_le_u32_e32 vcc, v36, v113
	v_add_u32_e32 v36, 56, v132
	s_nop 0
	v_cndmask_b32_e32 v62, v125, v62, vcc
	v_cmp_le_u32_e32 vcc, v36, v113
	v_add_u32_e32 v36, 25, v132
	v_exp_f32_e32 v137, v62
	v_cndmask_b32_e32 v154, v125, v46, vcc
	v_cmp_le_u32_e32 vcc, v36, v113
	v_add_u32_e32 v36, 57, v132
	s_nop 0
	v_cndmask_b32_e32 v155, v125, v63, vcc
	v_cmp_le_u32_e32 vcc, v36, v113
	v_add_u32_e32 v36, 26, v132
	v_exp_f32_e32 v63, v54
	v_cndmask_b32_e32 v158, v125, v47, vcc
	v_cmp_le_u32_e32 vcc, v36, v113
	v_add_u32_e32 v36, 58, v132
	v_exp_f32_e32 v139, v155
	v_cndmask_b32_e32 v64, v125, v64, vcc
	v_cmp_le_u32_e32 vcc, v36, v113
	v_add_u32_e32 v36, 27, v132
	v_exp_f32_e32 v141, v64
	v_cndmask_b32_e32 v159, v125, v48, vcc
	v_cmp_le_u32_e32 vcc, v36, v113
	v_add_u32_e32 v36, 59, v132
	s_nop 0
	v_cndmask_b32_e32 v160, v125, v65, vcc
	v_exp_f32_e32 v65, v142
	v_cmp_le_u32_e32 vcc, v36, v113
	v_max_f32_e32 v36, v50, v50
	v_max_f32_e32 v36, 0xff800000, v36
	v_max3_f32 v132, v36, v34, v35
	v_cvt_pk_bf16_f32 v34, v55, v57
	v_cvt_pk_bf16_f32 v35, v59, v61
	v_cvt_pk_bf16_f32 v36, v63, v65
	v_exp_f32_e32 v143, v160
	v_cndmask_b32_e32 v161, v125, v49, vcc
	s_waitcnt lgkmcnt(1)
; __device__ void attn_item(const Params& p, char* lds, int bh, int qi) {
;     ...
;     for (int r = 0; r < 16; ++r) { S0[r] = __builtin_amdgcn_exp2f(S0[r]); ps0 += S0[r]; }
; #pragma unroll
;     for (int sp = 0; sp < 2; ++sp) {
;       u32x4 pw;
;       pw.x = pk2(S0[8 * sp + 0], S0[8 * sp + 1]); pw.y = pk2(S0[8 * sp + 2], S0[8 * sp + 3]);
;       pw.z = pk2(S0[8 * sp + 4], S0[8 * sp + 5]); pw.w = pk2(S0[8 * sp + 6], S0[8 * sp + 7]);
;       const bf16x8 pb = __builtin_bit_cast(bf16x8, pw);
; #pragma unroll
;       for (int d = 0; d < 2; ++d) O[d] = __builtin_amdgcn_mfma_f32_32x32x16_bf16(*(const bf16x8*)(vs_ + d * 32 * LD + sp * 16), pb, O[d], 0, 0, 0);
;     }
; #pragma unroll
;     for (int r = 0; r < 16; r += 2) mx1 = fmaxf(fmaxf(mx1, S1[r]), S1[r + 1]);
; #pragma unroll
;     for (int r = 0; r < 16; ++r) { S1[r] = __builtin_amdgcn_exp2f(S1[r]); ps1 += S1[r]; }
; #pragma unroll
;     for (int sp = 0; sp < 2; ++sp) {
;       u32x4 pw;
;       pw.x = pk2(S1[8 * sp + 0], S1[8 * sp + 1]); pw.y = pk2(S1[8 * sp + 2], S1[8 * sp + 3]);
;       pw.z = pk2(S1[8 * sp + 4], S1[8 * sp + 5]); pw.w = pk2(S1[8 * sp + 6], S1[8 * sp + 7]);
;       const bf16x8 pb = __builtin_bit_cast(bf16x8, pw);
; #pragma unroll
;       for (int d = 0; d < 2; ++d) O[d] = __builtin_amdgcn_mfma_f32_32x32x16_bf16(*(const bf16x8*)(vs_ + d * 32 * LD + 32 + sp * 16), pb, O[d], 0, 0, 0);
;     }
;     lsum += ps0 + ps1;
;     ...
;     __builtin_amdgcn_sched_group_barrier(0x008, 4, 0);
; #pragma unroll
;     for (int i = 0; i < 4; ++i) { __builtin_amdgcn_sched_group_barrier(0x008, 1, 0); __builtin_amdgcn_sched_group_barrier(0x002, 12, 0); }
; #pragma unroll
;     for (int i = 0; i < 4; ++i) { __builtin_amdgcn_sched_group_barrier(0x008, 1, 0); __builtin_amdgcn_sched_group_barrier(0x002, 12, 0); }
;     __builtin_amdgcn_sched_group_barrier(0x008, 4, 0);
;     ...
;     float mx = fmaxf(mx0, mx1);
;     mx = fmaxf(mx, __shfl_xor(mx, 32));
;     if (__ballot(mx > 8.f) != 0ull) {
;       const float delta = (mx > 8.f) ? mx : 0.f;
;       const float alpha = __builtin_amdgcn_exp2f(-delta);
;       mref += delta;
;       lsum *= alpha;
; #pragma unroll
;       for (int d = 0; d < 2; ++d)
; #pragma unroll
;         for (int r = 0; r < 16; ++r) O[d][r] *= alpha;
;     }
	v_mfma_f32_32x32x16_bf16 v[18:33], v[128:131], v[34:37], v[18:33]
	v_exp_f32_e32 v129, v60
	v_exp_f32_e32 v131, v152
	ds_read_b128 v[42:45], v127 offset:18464
	ds_read_b128 v[46:49], v127 offset:18528
	v_exp_f32_e32 v128, v151
	v_exp_f32_e32 v130, v153
	v_cmp_lt_i32_e32 vcc, v156, v157
	s_waitcnt lgkmcnt(2)
	v_mfma_f32_32x32x16_bf16 v[2:17], v[38:41], v[34:37], v[2:17]
	ds_read_b128 v[38:41], v127 offset:23072
	ds_read_b128 v[50:53], v127 offset:18496
	v_cvt_pk_bf16_f32 v34, v133, v135
	v_cvt_pk_bf16_f32 v35, v129, v131
	v_cvt_pk_bf16_f32 v36, v137, v139
	v_cvt_pk_bf16_f32 v37, v141, v143
	s_waitcnt lgkmcnt(3)
	s_nop 0
	v_mfma_f32_32x32x16_bf16 v[18:33], v[42:45], v[34:37], v[18:33]
	v_max3_f32 v42, v132, v136, v54
	v_exp_f32_e32 v54, v90
	v_max3_f32 v42, v42, v142, v56
	v_exp_f32_e32 v56, v92
	v_max3_f32 v42, v42, v146, v58
	v_exp_f32_e32 v58, v134
	v_max3_f32 v42, v42, v149, v60
	s_waitcnt lgkmcnt(1)
	v_mfma_f32_32x32x16_bf16 v[2:17], v[38:41], v[34:37], v[2:17]
	v_max3_f32 v34, v90, s34, v92
	v_max3_f32 v34, v34, v134, v138
	v_max3_f32 v34, v34, v140, v144
	v_max3_f32 v34, v34, v145, v147
	v_max3_f32 v34, v34, v148, v150
	v_max3_f32 v34, v34, v151, v153
	v_exp_f32_e32 v60, v138
	v_max3_f32 v42, v42, v152, v62
	v_max3_f32 v149, v34, v154, v158
	v_pk_add_f32 v[34:35], v[54:55], 0 op_sel_hi:[1,0]
	v_exp_f32_e32 v62, v140
	v_max3_f32 v146, v42, v155, v64
	v_pk_add_f32 v[34:35], v[56:57], v[34:35]
	v_exp_f32_e32 v64, v144
	v_pk_add_f32 v[34:35], v[58:59], v[34:35]
	v_exp_f32_e32 v90, v145
	v_pk_add_f32 v[34:35], v[60:61], v[34:35]
	v_exp_f32_e32 v92, v147
	ds_read_b128 v[42:45], v127 offset:23104
	v_exp_f32_e32 v132, v148
	v_pk_add_f32 v[34:35], v[62:63], v[34:35]
	v_exp_f32_e32 v134, v150
	v_pk_add_f32 v[38:39], v[64:65], v[34:35]
	v_exp_f32_e32 v136, v154
	v_pk_add_f32 v[38:39], v[90:91], v[38:39]
	v_exp_f32_e32 v138, v158
	v_pk_add_f32 v[38:39], v[92:93], v[38:39]
	v_cvt_pk_bf16_f32 v34, v54, v56
	v_pk_add_f32 v[38:39], v[132:133], v[38:39]
	v_cvt_pk_bf16_f32 v35, v58, v60
	v_pk_add_f32 v[38:39], v[134:135], v[38:39]
	v_cvt_pk_bf16_f32 v36, v62, v64
	v_pk_add_f32 v[38:39], v[128:129], v[38:39]
	v_cvt_pk_bf16_f32 v37, v90, v92
	v_pk_add_f32 v[38:39], v[130:131], v[38:39]
	v_exp_f32_e32 v140, v159
	v_pk_add_f32 v[38:39], v[136:137], v[38:39]
	s_waitcnt lgkmcnt(1)
	v_mfma_f32_32x32x16_bf16 v[18:33], v[50:53], v[34:37], v[18:33]
	v_exp_f32_e32 v142, v161
	s_waitcnt lgkmcnt(0)
	v_mfma_f32_32x32x16_bf16 v[2:17], v[42:45], v[34:37], v[2:17]
	v_add_f32_e64 v34, v138, v38
	v_add_f32_e64 v35, v139, v39
	ds_read_b128 v[38:41], v127 offset:23136
	v_max3_f32 v44, v149, v159, v161
	v_pk_add_f32 v[42:43], v[140:141], v[34:35]
	v_cvt_pk_bf16_f32 v34, v132, v134
	v_cvt_pk_bf16_f32 v35, v128, v130
	v_cvt_pk_bf16_f32 v36, v136, v138
	v_cvt_pk_bf16_f32 v37, v140, v142
	v_max3_f32 v44, v146, v160, v44
	v_mfma_f32_32x32x16_bf16 v[18:33], v[46:49], v[34:37], v[18:33]
	v_mov_b32_e32 v45, v44
	v_add_f32_e64 v42, v142, v42
	v_add_f32_e64 v43, v143, v43
	s_waitcnt lgkmcnt(0)
	v_mfma_f32_32x32x16_bf16 v[2:17], v[38:41], v[34:37], v[2:17]
	v_add_f32_e32 v34, v42, v43
	v_add_f32_e32 v126, v126, v34
	s_nop 0
	v_permlane32_swap_b32_e32 v44, v45
	v_max_f32_e32 v34, v45, v45
	v_max_f32_e32 v34, v44, v34
	v_cmp_lt_f32_e32 vcc, s35, v34
	s_cbranch_vccz .LBB0_443
	s_nop 0
	v_cndmask_b32_e32 v35, 0, v34, vcc
	v_exp_f32_e64 v34, -v35
	v_add_f32_e32 v107, v107, v35
	v_mul_f32_e32 v126, v126, v34
	v_pk_mul_f32 v[32:33], v[32:33], v[34:35] op_sel_hi:[1,0]
	v_pk_mul_f32 v[30:31], v[30:31], v[34:35] op_sel_hi:[1,0]
	v_pk_mul_f32 v[28:29], v[28:29], v[34:35] op_sel_hi:[1,0]
	v_pk_mul_f32 v[26:27], v[26:27], v[34:35] op_sel_hi:[1,0]
	v_pk_mul_f32 v[24:25], v[24:25], v[34:35] op_sel_hi:[1,0]
	v_pk_mul_f32 v[22:23], v[22:23], v[34:35] op_sel_hi:[1,0]
	v_pk_mul_f32 v[20:21], v[20:21], v[34:35] op_sel_hi:[1,0]
	v_pk_mul_f32 v[18:19], v[18:19], v[34:35] op_sel_hi:[1,0]
	v_pk_mul_f32 v[16:17], v[16:17], v[34:35] op_sel_hi:[1,0]
	v_pk_mul_f32 v[14:15], v[14:15], v[34:35] op_sel_hi:[1,0]
	v_pk_mul_f32 v[12:13], v[12:13], v[34:35] op_sel_hi:[1,0]
	v_pk_mul_f32 v[10:11], v[10:11], v[34:35] op_sel_hi:[1,0]
	v_pk_mul_f32 v[8:9], v[8:9], v[34:35] op_sel_hi:[1,0]
	v_pk_mul_f32 v[6:7], v[6:7], v[34:35] op_sel_hi:[1,0]
	v_pk_mul_f32 v[4:5], v[4:5], v[34:35] op_sel_hi:[1,0]
	v_pk_mul_f32 v[2:3], v[2:3], v[34:35] op_sel_hi:[1,0]
